# rwkv_prep_item: MISC stage thread->(row,chunk) map made class-homogeneous per wave (tanh/sigmoid/plain) plus the logf dead-code trim, on top of v049
# speedup vs baseline: 1.0065x; 1.0065x over previous
; __device__ __forceinline__ float bflo(unsigned u) { return __uint_as_float(u << 16); }
; __device__ __forceinline__ float bfhi(unsigned u) { return __uint_as_float(u & 0xffff0000u); }
; #define LAS __attribute__((address_space(3)))
; __device__ __forceinline__ float bflo(unsigned u) { return __uint_as_float(u << 16); }
; __device__ __forceinline__ float bfhi(unsigned u) { return __uint_as_float(u & 0xffff0000u); }
; __device__ __forceinline__ int rwkv_tok(int b, int j) { if (j < LCTX) return TLAT + b * LCTX + j; const int s = j - LCTX; return b * LSEQ + (s & 31) * 64 + (s >> 5); }
; __device__ __forceinline__ void rwkv_prep_item(KArgs a, int l, int item, LAS unsigned char* lds, int tid, int lane, int wave) {
;     ...
;         const f32x4 m0 = *(const f32x4*)(mu + c8 * 8), m1 = *(const f32x4*)(mu + c8 * 8 + 4);
;         f32x4 x0 = (f32x4){bflo(c.x), bfhi(c.x), bflo(c.y), bfhi(c.y)}, x1 = (f32x4){bflo(c.z), bfhi(c.z), bflo(c.w), bfhi(c.w)};
;         const f32x4 s0 = (f32x4){bflo(p.x) + bflo(n.x), bfhi(p.x) + bfhi(n.x), bflo(p.y) + bflo(n.y), bfhi(p.y) + bfhi(n.y)}, s1 = (f32x4){bflo(p.z) + bflo(n.z), bfhi(p.z) + bfhi(n.z), bflo(p.w) + bflo(n.w), bfhi(p.w) + bfhi(n.w)};
;         x0 = x0 + (0.5f * s0 - x0) * m0; x1 = x1 + (0.5f * s1 - x1) * m1;
;         const int ch = c8 * 8, reg = ch >> 9; LAS float* dst = (reg == 0 ? RP : (reg == 1 ? KP : VP)) + i * RP_PITCH + (ch & 511);
;         *(LAS f32x4*)dst = x0; *(LAS f32x4*)(dst + 4) = x1; }
; #pragma unroll
;     for (int it_ = 0; it_ < 3; ++it_) { const int idx = tid + it_ * NTHR; if (idx >= 16 * 80) break; const int i = idx / 80, c4 = idx % 80, jj = j0 + i;
;         const bool hp = isctx ? (jj - 1 >= 0) : (jj - 1 >= LCTX), hn = isctx ? (jj + 1 < LCTX) : (jj + 1 < RJ);
;         f32x4 x = *(const f32x4*)(MISC + (size_t)rwkv_tok(b, jj) * 512 + 64 + c4 * 4); f32x4 p = (f32x4){0.f, 0.f, 0.f, 0.f}, n = p;
;         if (hp) p = *(const f32x4*)(MISC + (size_t)rwkv_tok(b, jj - 1) * 512 + 64 + c4 * 4);
;         if (hn) n = *(const f32x4*)(MISC + (size_t)rwkv_tok(b, jj + 1) * 512 + 64 + c4 * 4);
.LBB0_708:
	s_or_b64 exec, exec, s[0:1]
	v_lshl_add_u64 v[192:193], v[178:179], 2, s[44:45]
	global_load_dwordx4 v[188:191], v[192:193], off
	s_nop 0
	global_load_dwordx4 v[192:195], v[192:193], off offset:16
	v_and_b32_e32 v208, 0xffffffc0, v187
	s_waitcnt vmcnt(2)
	v_lshlrev_b32_e32 v196, 16, v162
	v_and_b32_e32 v197, 0xffff0000, v162
	v_lshlrev_b32_e32 v162, 16, v163
	v_and_b32_e32 v163, 0xffff0000, v163
	v_lshlrev_b32_e32 v198, 16, v164
	v_and_b32_e32 v199, 0xffff0000, v164
	v_lshlrev_b32_e32 v200, 16, v165
	v_and_b32_e32 v201, 0xffff0000, v165
	v_lshlrev_b32_e32 v164, 16, v166
	v_and_b32_e32 v165, 0xffff0000, v166
	v_lshlrev_b32_e32 v202, 16, v170
	v_and_b32_e32 v203, 0xffff0000, v170
	v_lshlrev_b32_e32 v166, 16, v167
	v_and_b32_e32 v167, 0xffff0000, v167
	v_lshlrev_b32_e32 v170, 16, v171
	v_and_b32_e32 v171, 0xffff0000, v171
	v_lshlrev_b32_e32 v204, 16, v168
	v_and_b32_e32 v205, 0xffff0000, v168
	v_lshlrev_b32_e32 v206, 16, v172
	v_and_b32_e32 v207, 0xffff0000, v172
	v_lshlrev_b32_e32 v168, 16, v169
	v_and_b32_e32 v169, 0xffff0000, v169
	v_lshlrev_b32_e32 v172, 16, v173
	v_and_b32_e32 v173, 0xffff0000, v173
	v_cmp_eq_u32_e32 vcc, 64, v208
	v_and_b32_e32 v209, 0x1f8, v178
	v_pk_add_f32 v[164:165], v[164:165], v[202:203]
	v_pk_add_f32 v[166:167], v[166:167], v[170:171]
	v_pk_add_f32 v[170:171], v[204:205], v[206:207]
	v_pk_add_f32 v[168:169], v[168:169], v[172:173]
	v_xor_b32_e32 v173, 0x80000000, v197
	v_xor_b32_e32 v172, 0x80000000, v196
	v_xor_b32_e32 v179, 0x80000000, v163
	v_xor_b32_e32 v178, 0x80000000, v162
	v_xor_b32_e32 v203, 0x80000000, v199
	v_xor_b32_e32 v202, 0x80000000, v198
	v_cndmask_b32_e32 v206, v230, v231, vcc
	s_movk_i32 s0, 0x810
	v_pk_fma_f32 v[172:173], v[164:165], 0.5, v[172:173] op_sel_hi:[1,0,1]
	v_pk_fma_f32 v[164:165], v[166:167], 0.5, v[178:179] op_sel_hi:[1,0,1]
	v_pk_fma_f32 v[166:167], v[170:171], 0.5, v[202:203] op_sel_hi:[1,0,1]
	v_add_u32_e32 v170, 0, v206
	v_cmp_gt_u32_e32 vcc, 64, v187
	v_mul_lo_u32 v186, v186, s0
	v_xor_b32_e32 v205, 0x80000000, v201
	v_xor_b32_e32 v204, 0x80000000, v200
	v_lshlrev_b32_e32 v207, 2, v209
	v_cndmask_b32_e64 v170, v170, 0, vcc
	s_movk_i32 s0, 0x500
	v_pk_fma_f32 v[168:169], v[168:169], 0.5, v[204:205] op_sel_hi:[1,0,1]
	v_add3_u32 v170, v170, v186, v207
	v_cmp_gt_i32_e32 vcc, s0, v183
	s_waitcnt vmcnt(1)
	v_pk_fma_f32 v[164:165], v[190:191], v[164:165], v[162:163]
	v_pk_fma_f32 v[162:163], v[188:189], v[172:173], v[196:197]
	s_waitcnt vmcnt(0)
	v_pk_fma_f32 v[168:169], v[194:195], v[168:169], v[200:201]
	v_pk_fma_f32 v[166:167], v[192:193], v[166:167], v[198:199]
	ds_write_b128 v170, v[162:165]
	ds_write_b128 v170, v[166:169] offset:16
	s_and_saveexec_b64 s[46:47], vcc
	s_cbranch_execz .LBB0_826
	s_mov_b32 s0, 0x66666667
	v_mul_hi_i32 v162, v183, s0
	v_lshrrev_b32_e32 v163, 31, v162
	v_ashrrev_i32_e32 v162, 5, v162
	v_lshrrev_b32_e32 v186, 5, v183
	v_add_u32_e32 v188, s6, v186
	s_movk_i32 s0, 0xff
	v_cmp_lt_i32_e32 vcc, s0, v188
	s_and_saveexec_b64 s[0:1], vcc
	s_xor_b64 s[0:1], exec, s[0:1]
	v_lshlrev_b32_e32 v163, 6, v188
	v_add_u32_e32 v162, 0xffffff00, v188
	v_and_b32_e32 v163, 0x7c0, v163
	v_or_b32_e32 v163, s9, v163
	v_lshrrev_b32_e32 v162, 5, v162
	v_add_u32_e32 v162, v163, v162
	s_andn2_saveexec_b64 s[0:1], s[0:1]
	v_add_u32_e32 v162, s10, v188
	s_or_b64 exec, exec, s[0:1]
	s_movk_i32 s0, 0x50
	v_mul_lo_u32 v163, v186, s0
	v_and_b32_e32 v187, 31, v183
	v_ashrrev_i32_e32 v163, 31, v162
	v_lshlrev_b64 v[162:163], 11, v[162:163]
	v_lshlrev_b32_e32 v178, 2, v187
	v_lshl_add_u64 v[162:163], s[38:39], 0, v[162:163]
	v_ashrrev_i32_e32 v179, 31, v178
	v_lshl_add_u64 v[162:163], v[178:179], 2, v[162:163]
	global_load_dwordx4 v[162:165], v[162:163], off offset:256
	v_cmp_lt_i32_e32 vcc, s11, v188
	v_mov_b32_e32 v169, 0
	v_mov_b32_e32 v168, 0
	v_mov_b32_e32 v167, 0
	v_mov_b32_e32 v166, 0
	s_and_saveexec_b64 s[0:1], vcc
	s_cbranch_execz .LBB0_719
	s_movk_i32 s2, 0x100
	v_add_u32_e32 v167, -1, v188
	v_cmp_lt_u32_e32 vcc, s2, v188
	s_and_saveexec_b64 s[2:3], vcc
	s_xor_b64 s[2:3], exec, s[2:3]
	v_add_u32_e32 v166, 0xfffffeff, v188
	v_lshlrev_b32_e32 v167, 6, v167
	v_and_b32_e32 v167, 0x7c0, v167
	v_lshrrev_b32_e32 v166, 5, v166
	v_add3_u32 v166, v166, s9, v167
	s_andn2_saveexec_b64 s[2:3], s[2:3]
	v_add_u32_e32 v166, s10, v167
	s_or_b64 exec, exec, s[2:3]
	v_ashrrev_i32_e32 v167, 31, v166
	v_lshlrev_b64 v[166:167], 11, v[166:167]
	v_lshl_add_u64 v[166:167], s[38:39], 0, v[166:167]
	v_lshl_add_u64 v[166:167], v[178:179], 2, v[166:167]
	global_load_dwordx4 v[166:169], v[166:167], off offset:256

; #define LAS __attribute__((address_space(3)))
; __device__ __forceinline__ unsigned pk2(float lo, float hi) { const bf16x2_t r = __builtin_convertvector((f32x2){lo, hi}, bf16x2_t); return __builtin_bit_cast(unsigned, r); }
; __device__ __forceinline__ float sigmoidf_(float x) { return __builtin_amdgcn_rcpf(1.f + __expf(-x)); }
; __device__ __forceinline__ int rwkv_tok(int b, int j) { if (j < LCTX) return TLAT + b * LCTX + j; const int s = j - LCTX; return b * LSEQ + (s & 31) * 64 + (s >> 5); }
; __device__ __forceinline__ void rwkv_prep_item(KArgs a, int l, int item, LAS unsigned char* lds, int tid, int lane, int wave) {
;     ...
;     for (int it_ = 0; it_ < 3; ++it_) { const int idx = tid + it_ * NTHR; if (idx >= 16 * 80) break; const int i = idx / 80, c4 = idx % 80, jj = j0 + i;
;         const bool hp = isctx ? (jj - 1 >= 0) : (jj - 1 >= LCTX), hn = isctx ? (jj + 1 < LCTX) : (jj + 1 < RJ);
;         f32x4 x = *(const f32x4*)(MISC + (size_t)rwkv_tok(b, jj) * 512 + 64 + c4 * 4); f32x4 p = (f32x4){0.f, 0.f, 0.f, 0.f}, n = p;
;         if (hp) p = *(const f32x4*)(MISC + (size_t)rwkv_tok(b, jj - 1) * 512 + 64 + c4 * 4);
;         if (hn) n = *(const f32x4*)(MISC + (size_t)rwkv_tok(b, jj + 1) * 512 + 64 + c4 * 4);
;         x = x + (0.5f * (p + n) - x) * *(const f32x4*)(mu + 1536 + c4 * 4);
;         const int m = c4 * 4;
;         if (m < 128) x = (f32x4){tanhf(x.x), tanhf(x.y), tanhf(x.z), tanhf(x.w)}; else if (m >= 192) x = (f32x4){sigmoidf_(x.x), sigmoidf_(x.y), sigmoidf_(x.z), sigmoidf_(x.w)};
;         *(LAS v2u*)(ACT + i * ACT_PITCH + m) = (v2u){pk2(x.x, x.y), pk2(x.z, x.w)}; }
.LBB0_747:
	s_or_b64 exec, exec, s[2:3]
	s_movk_i32 s2, 0x290
	v_cvt_pk_bf16_f32 v162, v162, v163
	v_cvt_pk_bf16_f32 v163, v164, v165
	v_mul_lo_u32 v164, v186, s2
	v_lshlrev_b32_e32 v165, 1, v178
	v_readlane_b32 s2, v253, 56
	s_nop 1
	v_add3_u32 v164, s2, v164, v165
	s_movk_i32 s2, 0x300
	v_cmp_gt_i32_e32 vcc, s2, v183
	ds_write_b64 v164, v[162:163]
	s_and_b64 exec, exec, vcc
	s_cbranch_execz .LBB0_826
	s_mov_b32 s2, 0x66666667
	v_mul_hi_i32 v162, v185, s2
	v_lshrrev_b32_e32 v163, 31, v162
	v_ashrrev_i32_e32 v162, 5, v162
	v_lshrrev_b32_e32 v162, 4, v183
	v_add_u32_e32 v163, 0xffffff00, v183
	v_lshrrev_b32_e32 v163, 5, v163
	v_cmp_gt_u32_e32 vcc, 0x100, v183
	s_nop 1
	v_cndmask_b32_e32 v186, v163, v162, vcc
	v_add_u32_e32 v187, s6, v186
	s_movk_i32 s2, 0xff
	v_cmp_lt_i32_e32 vcc, s2, v187
	s_and_saveexec_b64 s[2:3], vcc
	s_xor_b64 s[2:3], exec, s[2:3]
	v_lshlrev_b32_e32 v163, 6, v187
	v_add_u32_e32 v162, 0xffffff00, v187
	v_and_b32_e32 v163, 0x7c0, v163
	v_or_b32_e32 v163, s9, v163
	v_lshrrev_b32_e32 v162, 5, v162
	v_add_u32_e32 v162, v163, v162
	s_andn2_saveexec_b64 s[2:3], s[2:3]
	v_add_u32_e32 v162, s10, v187
	s_or_b64 exec, exec, s[2:3]
	s_movk_i32 s2, 0x50
	v_mul_lo_u32 v163, v186, s2
	v_and_b32_e32 v163, 15, v183
	v_add_u32_e32 v163, 32, v163
	v_and_b32_e32 v164, 31, v183
	v_add_u32_e32 v164, 48, v164
	v_cmp_gt_u32_e32 vcc, 0x100, v183
	s_nop 1
	v_cndmask_b32_e32 v185, v164, v163, vcc
	v_ashrrev_i32_e32 v163, 31, v162
	v_lshlrev_b64 v[162:163], 11, v[162:163]
	v_lshlrev_b32_e32 v178, 2, v185
	v_lshl_add_u64 v[162:163], s[38:39], 0, v[162:163]
	v_ashrrev_i32_e32 v179, 31, v178
	v_lshl_add_u64 v[162:163], v[178:179], 2, v[162:163]
	global_load_dwordx4 v[162:165], v[162:163], off offset:256
	v_cmp_lt_i32_e32 vcc, s11, v187
	v_mov_b32_e32 v169, 0
	v_mov_b32_e32 v168, 0
	v_mov_b32_e32 v167, 0
	v_mov_b32_e32 v166, 0
	s_and_saveexec_b64 s[2:3], vcc
	s_cbranch_execz .LBB0_758
	s_movk_i32 s4, 0x100
	v_add_u32_e32 v167, -1, v187
	v_cmp_lt_u32_e32 vcc, s4, v187
	s_and_saveexec_b64 s[4:5], vcc
	s_xor_b64 s[4:5], exec, s[4:5]
	v_add_u32_e32 v166, 0xfffffeff, v187
	v_lshlrev_b32_e32 v167, 6, v167
	v_and_b32_e32 v167, 0x7c0, v167
	v_lshrrev_b32_e32 v166, 5, v166
	v_add3_u32 v166, v166, s9, v167
	s_andn2_saveexec_b64 s[4:5], s[4:5]
	v_add_u32_e32 v166, s10, v167
	s_or_b64 exec, exec, s[4:5]
	v_ashrrev_i32_e32 v167, 31, v166
	v_lshlrev_b64 v[166:167], 11, v[166:167]
	v_lshl_add_u64 v[166:167], s[38:39], 0, v[166:167]
	v_lshl_add_u64 v[166:167], v[178:179], 2, v[166:167]
	global_load_dwordx4 v[166:169], v[166:167], off offset:256

; #define LAS __attribute__((address_space(3)))
; __device__ __forceinline__ unsigned pk2(float lo, float hi) { const bf16x2_t r = __builtin_convertvector((f32x2){lo, hi}, bf16x2_t); return __builtin_bit_cast(unsigned, r); }
; __device__ __forceinline__ float sigmoidf_(float x) { return __builtin_amdgcn_rcpf(1.f + __expf(-x)); }
; __device__ __forceinline__ int rwkv_tok(int b, int j) { if (j < LCTX) return TLAT + b * LCTX + j; const int s = j - LCTX; return b * LSEQ + (s & 31) * 64 + (s >> 5); }
; __device__ __forceinline__ void rwkv_prep_item(KArgs a, int l, int item, LAS unsigned char* lds, int tid, int lane, int wave) {
;     ...
;     for (int it_ = 0; it_ < 3; ++it_) { const int idx = tid + it_ * NTHR; if (idx >= 16 * 80) break; const int i = idx / 80, c4 = idx % 80, jj = j0 + i;
;         const bool hp = isctx ? (jj - 1 >= 0) : (jj - 1 >= LCTX), hn = isctx ? (jj + 1 < LCTX) : (jj + 1 < RJ);
;         f32x4 x = *(const f32x4*)(MISC + (size_t)rwkv_tok(b, jj) * 512 + 64 + c4 * 4); f32x4 p = (f32x4){0.f, 0.f, 0.f, 0.f}, n = p;
;         if (hp) p = *(const f32x4*)(MISC + (size_t)rwkv_tok(b, jj - 1) * 512 + 64 + c4 * 4);
;         if (hn) n = *(const f32x4*)(MISC + (size_t)rwkv_tok(b, jj + 1) * 512 + 64 + c4 * 4);
;         x = x + (0.5f * (p + n) - x) * *(const f32x4*)(mu + 1536 + c4 * 4);
;         const int m = c4 * 4;
;         if (m < 128) x = (f32x4){tanhf(x.x), tanhf(x.y), tanhf(x.z), tanhf(x.w)}; else if (m >= 192) x = (f32x4){sigmoidf_(x.x), sigmoidf_(x.y), sigmoidf_(x.z), sigmoidf_(x.w)};
;         *(LAS v2u*)(ACT + i * ACT_PITCH + m) = (v2u){pk2(x.x, x.y), pk2(x.z, x.w)}; }
.LBB0_786:
	s_or_b64 exec, exec, s[2:3]
	s_movk_i32 s2, 0x290
	v_cvt_pk_bf16_f32 v162, v162, v163
	v_cvt_pk_bf16_f32 v163, v164, v165
	v_mul_lo_u32 v164, v186, s2
	v_lshlrev_b32_e32 v165, 1, v178
	v_readlane_b32 s2, v253, 56
	s_nop 1
	v_add3_u32 v164, s2, v164, v165
	s_movk_i32 s2, 0x100
	v_cmp_gt_i32_e32 vcc, s2, v183
	ds_write_b64 v164, v[162:163]
	s_and_b64 exec, exec, vcc
	s_cbranch_execz .LBB0_826
	s_mov_b32 s2, 0x66666667
	v_mul_hi_i32 v162, v177, s2
	v_lshrrev_b32_e32 v163, 31, v162
	v_ashrrev_i32_e32 v162, 5, v162
	v_lshrrev_b32_e32 v183, 5, v183
	v_add_u32_e32 v183, 8, v183
	v_add_u32_e32 v185, s6, v183
	s_movk_i32 s2, 0xff
	v_cmp_lt_i32_e32 vcc, s2, v185
	s_and_saveexec_b64 s[2:3], vcc
	s_xor_b64 s[2:3], exec, s[2:3]
	v_lshlrev_b32_e32 v163, 6, v185
	v_add_u32_e32 v162, 0xffffff00, v185
	v_and_b32_e32 v163, 0x7c0, v163
	v_or_b32_e32 v163, s9, v163
	v_lshrrev_b32_e32 v162, 5, v162
	v_add_u32_e32 v162, v163, v162
	s_andn2_saveexec_b64 s[2:3], s[2:3]
	v_add_u32_e32 v162, s10, v185
	s_or_b64 exec, exec, s[2:3]
	s_movk_i32 s2, 0x50
	v_mul_lo_u32 v163, v183, s2
	v_and_b32_e32 v177, 31, v177
	v_add_u32_e32 v177, 48, v177
	v_ashrrev_i32_e32 v163, 31, v162
	v_lshlrev_b64 v[162:163], 11, v[162:163]
	v_lshlrev_b32_e32 v178, 2, v177
	v_lshl_add_u64 v[162:163], s[38:39], 0, v[162:163]
	v_ashrrev_i32_e32 v179, 31, v178
	v_lshl_add_u64 v[162:163], v[178:179], 2, v[162:163]
	global_load_dwordx4 v[162:165], v[162:163], off offset:256
	v_cmp_lt_i32_e32 vcc, s11, v185
	v_mov_b32_e32 v169, 0
	v_mov_b32_e32 v168, 0
	v_mov_b32_e32 v167, 0
	v_mov_b32_e32 v166, 0
	s_and_saveexec_b64 s[2:3], vcc
	s_cbranch_execz .LBB0_797
	s_movk_i32 s4, 0x100
	v_add_u32_e32 v167, -1, v185
	v_cmp_lt_u32_e32 vcc, s4, v185
	s_and_saveexec_b64 s[4:5], vcc
	s_xor_b64 s[4:5], exec, s[4:5]
	v_add_u32_e32 v166, 0xfffffeff, v185
	v_lshlrev_b32_e32 v167, 6, v167
	v_and_b32_e32 v167, 0x7c0, v167
	v_lshrrev_b32_e32 v166, 5, v166
	v_add3_u32 v166, v166, s9, v167
	s_andn2_saveexec_b64 s[4:5], s[4:5]
	v_add_u32_e32 v166, s10, v167
	s_or_b64 exec, exec, s[4:5]
	v_ashrrev_i32_e32 v167, 31, v166
	v_lshlrev_b64 v[166:167], 11, v[166:167]
	v_lshl_add_u64 v[166:167], s[38:39], 0, v[166:167]
	v_lshl_add_u64 v[166:167], v[178:179], 2, v[166:167]
	global_load_dwordx4 v[166:169], v[166:167], off offset:256
